# k54: k52 with the attention tile loop's single iteration-top wait vmcnt(4) restored (k42 placement) to compare against the split top/mid waits
# baseline (speedup 1.0000x reference)
; #define LAS __attribute__((address_space(3)))
; template <bool BAND>
; __device__ __forceinline__ void tile_body(f32x16* o, float& l_reg, const bf16x8* qr, const LAS unsigned char* kbs, const LAS float* wb, int vb, float ci, int hi, int keybase, int qabs) {
;     f32x16 p0, p1;
; #pragma unroll
;     for (int g4 = 0; g4 < 4; ++g4) {
;         const f32x4 ba = *(const LAS f32x4*)(wb + 8 * g4 + 4 * hi) + ci, bb = *(const LAS f32x4*)(wb + 32 + 8 * g4 + 4 * hi) + ci;
; #pragma unroll
;         for (int e = 0; e < 4; ++e) { p0[4 * g4 + e] = ba[e]; p1[4 * g4 + e] = bb[e]; }
;     }
; #pragma unroll
;     for (int d0 = 0; d0 < 4; ++d0) {
;         const bf16x8 b0 = *(const LAS bf16x8*)(kbs + d0 * 2048), b1 = *(const LAS bf16x8*)(kbs + d0 * 2048 + 512);
;         p0 = __builtin_amdgcn_mfma_f32_32x32x16_bf16(b0, qr[d0], p0, 0, 0, 0); p1 = __builtin_amdgcn_mfma_f32_32x32x16_bf16(b1, qr[d0], p1, 0, 0, 0); }
;     if (BAND) {
; #pragma unroll
;         for (int r = 0; r < 16; ++r) { const int key = keybase + 8 * (r >> 2) + (r & 3); if (key > qabs) p0[r] = -INFINITY; if (key + 32 > qabs) p1[r] = -INFINITY; }
.LBB0_777:
	s_waitcnt lgkmcnt(0)
	s_barrier
	s_waitcnt vmcnt(4)
	s_nop 1
	v_add_f32_dpp v0, v140, v140 row_shl:1 row_mask:0xf bank_mask:0xf bound_ctrl:1
	s_nop 1
	v_add_f32_dpp v0, v0, v0 row_shl:2 row_mask:0xf bank_mask:0xf bound_ctrl:1
	s_nop 1
	v_add_f32_dpp v0, v0, v0 row_shl:4 row_mask:0xf bank_mask:0xf bound_ctrl:1
	s_nop 1
	v_add_f32_dpp v0, v0, v0 row_shl:8 row_mask:0xf bank_mask:0xf bound_ctrl:1
	s_nop 0
	v_readlane_b32 s28, v0, 16
	v_readlane_b32 s67, v0, 32
	v_readlane_b32 s66, v0, 48
	s_nop 0
	v_mul_f32_e32 v149, s67, v192
	v_fmac_f32_e32 v149, s28, v191
	v_fmac_f32_e32 v149, s66, v193
	v_add_f32_e32 v149, v0, v149
	s_xor_b32 s74, s70, 1
	v_add_f32_e32 v0, v150, v149
	s_lshl_b32 s12, s74, 8
	v_sub_f32_e32 v0, v0, v140
	s_add_i32 s71, s53, s12
	s_lshl_b32 s78, s74, 14
	s_max_i32 s12, s48, 4
	v_mul_f32_e32 v140, 0x3fb8aa3b, v0
	v_lshl_add_u32 v0, v137, 2, s71
	v_readfirstlane_b32 s76, v149
	v_add_u32_e32 v149, s78, v143
	s_add_i32 s28, s12, -4
	ds_write_b32 v0, v140 offset:32768
	ds_write_b128 v149, v[66:69]
	ds_write_b128 v149, v[74:77] offset:8192
	s_lshl_b64 s[12:13], s[28:29], 11
	s_waitcnt lgkmcnt(0)
	v_lshl_add_u64 v[66:67], v[110:111], 0, s[12:13]
	s_lshl_b64 s[12:13], s[28:29], 16
	global_load_dword v140, v[66:67], off
	v_lshl_add_u64 v[74:75], v[106:107], 0, s[12:13]
	global_load_dwordx4 v[66:69], v[74:75], off
	s_nop 0
	v_lshl_add_u64 v[152:153], v[108:109], 0, s[12:13]
	s_not_b64 s[12:13], s[58:59]
	global_load_dwordx4 v[74:77], v[152:153], off
	s_andn2_b64 vcc, exec, s[58:59]
	s_cbranch_vccnz .LBB0_792
	s_and_b64 vcc, exec, s[98:99]
	s_cbranch_vccnz .LBB0_792
	s_sub_i32 s28, s75, 64
	s_cmp_gt_i32 s28, s73
	s_cbranch_scc1 .LBB0_792
	s_lshl_b32 s64, s70, 8
	s_lshl_b32 s28, s70, 14
	s_add_i32 s66, s53, s64
	s_cmp_lt_i32 s48, s72
	v_add_u32_e32 v151, s28, v144
	s_mov_b64 s[64:65], -1
	v_add_u32_e32 v152, s28, v145
	v_lshl_add_u32 v153, v142, 2, s66
	s_cbranch_scc1 .LBB0_789
	ds_read_b128 v[34:37], v153 offset:32768
	ds_read_b128 v[38:41], v153 offset:32800
	ds_read_b128 v[42:45], v153 offset:32832
	ds_read_b128 v[46:49], v153 offset:32864
	ds_read_b128 v[50:53], v153 offset:32896
	ds_read_b128 v[54:57], v153 offset:32928
	ds_read_b128 v[58:61], v153 offset:32960
	ds_read_b128 v[62:65], v153 offset:32992
	ds_read_b128 v[154:157], v152
	ds_read_b128 v[158:161], v152 offset:512
	s_waitcnt lgkmcnt(4)
	ds_read_b128 v[210:213], v152 offset:2048
	ds_read_b128 v[214:217], v152 offset:2560
	ds_read_b128 v[218:221], v152 offset:4096
	ds_read_b128 v[222:225], v152 offset:4608
	ds_read_b128 v[226:229], v152 offset:6656
	ds_read_b128 v[230:233], v152 offset:6144
	v_pk_add_f32 v[56:57], v[118:119], v[56:57]
	s_waitcnt lgkmcnt(9)
	v_pk_add_f32 v[60:61], v[122:123], v[60:61]
	s_waitcnt lgkmcnt(8)
	v_pk_add_f32 v[64:65], v[126:127], v[64:65]
	v_pk_add_f32 v[52:53], v[114:115], v[52:53]
	v_pk_add_f32 v[62:63], v[124:125], v[62:63]
	v_pk_add_f32 v[58:59], v[120:121], v[58:59]
	v_pk_add_f32 v[54:55], v[116:117], v[54:55]
	v_pk_add_f32 v[50:51], v[112:113], v[50:51]
	v_pk_add_f32 v[48:49], v[126:127], v[48:49]
	v_pk_add_f32 v[44:45], v[122:123], v[44:45]
	v_pk_add_f32 v[40:41], v[118:119], v[40:41]
	v_pk_add_f32 v[36:37], v[114:115], v[36:37]
	v_pk_add_f32 v[46:47], v[124:125], v[46:47]
	v_pk_add_f32 v[42:43], v[120:121], v[42:43]
	v_pk_add_f32 v[38:39], v[116:117], v[38:39]
	v_pk_add_f32 v[34:35], v[112:113], v[34:35]
	s_waitcnt lgkmcnt(6)
	v_mfma_f32_32x32x16_bf16 v[50:65], v[158:161], v[94:97], v[50:65]
	v_mfma_f32_32x32x16_bf16 v[34:49], v[154:157], v[94:97], v[34:49]
	s_waitcnt lgkmcnt(4)
	v_mfma_f32_32x32x16_bf16 v[50:65], v[214:217], v[98:101], v[50:65]
	v_mfma_f32_32x32x16_bf16 v[34:49], v[210:213], v[98:101], v[34:49]
	s_waitcnt lgkmcnt(2)
	v_mfma_f32_32x32x16_bf16 v[50:65], v[222:225], v[102:105], v[50:65]
	v_mfma_f32_32x32x16_bf16 v[34:49], v[218:221], v[102:105], v[34:49]
	s_waitcnt lgkmcnt(1)
	v_mfma_f32_32x32x16_bf16 v[50:65], v[226:229], v[90:93], v[50:65]
	v_add_u32_e32 v154, s75, v142
	v_subrev_u32_e32 v156, 32, v154
	v_subrev_u32_e32 v155, 64, v154
	v_cmp_le_i32_e32 vcc, v156, v147
	s_waitcnt lgkmcnt(0)
; __device__ __forceinline__ void pv(f32x16* o, int vb, bf16x8 pa0, bf16x8 pa1, bf16x8 pa2, bf16x8 pa3) {
; #pragma unroll
;     for (int d0 = 0; d0 < 2; ++d0) { s16x4 lo[4], hi[4];
; #pragma unroll
;         for (int ks = 0; ks < 4; ++ks) {
;             asm volatile("ds_read_b64_tr_b16 %0,%1 offset:%c2" : "=&v"(lo[ks]) : "v"(vb), "i"(d0 * 4096 + ks * 1024) : "memory");
;             asm volatile("ds_read_b64_tr_b16 %0,%1 offset:%c2" : "=&v"(hi[ks]) : "v"(vb), "i"(d0 * 4096 + ks * 1024 + 512) : "memory"); }
;         asm volatile("s_waitcnt lgkmcnt(0)" ::: "memory"); __builtin_amdgcn_sched_barrier(0);
;     ...
;         o[d0] = __builtin_amdgcn_mfma_f32_32x32x16_bf16(pa0, PK(0), o[d0], 0, 0, 0);
;         o[d0] = __builtin_amdgcn_mfma_f32_32x32x16_bf16(pa1, PK(1), o[d0], 0, 0, 0);
;         o[d0] = __builtin_amdgcn_mfma_f32_32x32x16_bf16(pa2, PK(2), o[d0], 0, 0, 0);
;         o[d0] = __builtin_amdgcn_mfma_f32_32x32x16_bf16(pa3, PK(3), o[d0], 0, 0, 0);
; template <bool BAND>
; __device__ __forceinline__ void tile_body(f32x16* o, float& l_reg, const bf16x8* qr, const LAS unsigned char* kbs, const LAS float* wb, int vb, float ci, int hi, int keybase, int qabs) {
;     ...
;         for (int r = 0; r < 16; ++r) { const int key = keybase + 8 * (r >> 2) + (r & 3); if (key > qabs) p0[r] = -INFINITY; if (key + 32 > qabs) p1[r] = -INFINITY; }
;     }
;     f32x2 s2 = {0.f, 0.f};
; #pragma unroll
;     for (int r = 0; r < 16; r += 2) {
;         p0[r] = __builtin_amdgcn_exp2f(p0[r]); p0[r + 1] = __builtin_amdgcn_exp2f(p0[r + 1]); p1[r] = __builtin_amdgcn_exp2f(p1[r]); p1[r + 1] = __builtin_amdgcn_exp2f(p1[r + 1]);
;         s2 += (f32x2){p0[r], p0[r + 1]}; s2 += (f32x2){p1[r], p1[r + 1]}; }
;     l_reg += s2.x + s2.y;
;     u32x4 pw0, pw1, pw2, pw3;
;     pw0 = (u32x4){cvtpk(p0[0], p0[1]), cvtpk(p0[2], p0[3]), cvtpk(p0[4], p0[5]), cvtpk(p0[6], p0[7])};
;     pw1 = (u32x4){cvtpk(p0[8], p0[9]), cvtpk(p0[10], p0[11]), cvtpk(p0[12], p0[13]), cvtpk(p0[14], p0[15])};
;     pw2 = (u32x4){cvtpk(p1[0], p1[1]), cvtpk(p1[2], p1[3]), cvtpk(p1[4], p1[5]), cvtpk(p1[6], p1[7])};
;     pw3 = (u32x4){cvtpk(p1[8], p1[9]), cvtpk(p1[10], p1[11]), cvtpk(p1[12], p1[13]), cvtpk(p1[14], p1[15])};
;     pv(o, vb, __builtin_bit_cast(bf16x8, pw0), __builtin_bit_cast(bf16x8, pw1), __builtin_bit_cast(bf16x8, pw2), __builtin_bit_cast(bf16x8, pw3));
	v_mfma_f32_32x32x16_bf16 v[34:49], v[230:233], v[90:93], v[34:49]
	s_nop 5
	v_cndmask_b32_e32 v50, v134, v50, vcc
	v_cmp_lt_i32_e32 vcc, v155, v147
	s_nop 3
	v_cndmask_b32_e32 v35, v134, v35, vcc
	v_cmp_le_i32_e32 vcc, v155, v147
	v_subrev_u32_e32 v155, 31, v154
	v_exp_f32_e32 v35, v35
	v_cndmask_b32_e32 v34, v134, v34, vcc
	v_cmp_le_i32_e32 vcc, v155, v147
	v_subrev_u32_e32 v155, 62, v154
	v_exp_f32_e32 v34, v34
	v_cndmask_b32_e32 v51, v134, v51, vcc
	v_cmp_le_i32_e32 vcc, v155, v147
	s_nop 1
	v_cndmask_b32_e32 v155, v134, v36, vcc
	v_subrev_u32_e32 v36, 30, v154
	v_cmp_le_i32_e32 vcc, v36, v147
	v_subrev_u32_e32 v36, 61, v154
	s_nop 0
	v_cndmask_b32_e32 v52, v134, v52, vcc
	v_cmp_le_i32_e32 vcc, v36, v147
	v_subrev_u32_e32 v36, 29, v154
	s_nop 0
	v_cndmask_b32_e32 v156, v134, v37, vcc
	v_cmp_le_i32_e32 vcc, v36, v147
	v_subrev_u32_e32 v36, 56, v154
	v_exp_f32_e32 v37, v51
	v_cndmask_b32_e32 v53, v134, v53, vcc
	v_cmp_le_i32_e32 vcc, v36, v147
	v_subrev_u32_e32 v36, 24, v154
	s_nop 0
	v_cndmask_b32_e32 v157, v134, v38, vcc
	v_cmp_le_i32_e32 vcc, v36, v147
	v_subrev_u32_e32 v36, 55, v154
	v_exp_f32_e32 v38, v155
	v_cndmask_b32_e32 v54, v134, v54, vcc
	v_cmp_le_i32_e32 vcc, v36, v147
	v_subrev_u32_e32 v36, 23, v154
	s_nop 0
	v_cndmask_b32_e32 v158, v134, v39, vcc
	v_cmp_le_i32_e32 vcc, v36, v147
	v_subrev_u32_e32 v36, 54, v154
	v_exp_f32_e32 v39, v156
	v_cndmask_b32_e32 v55, v134, v55, vcc
	v_cmp_le_i32_e32 vcc, v36, v147
	v_subrev_u32_e32 v36, 22, v154
	v_cvt_pk_bf16_f32 v156, v34, v35
	v_cndmask_b32_e32 v159, v134, v40, vcc
	v_cmp_le_i32_e32 vcc, v36, v147
	v_subrev_u32_e32 v36, 53, v154
	v_exp_f32_e32 v40, v52
	v_cndmask_b32_e32 v56, v134, v56, vcc
	v_cmp_le_i32_e32 vcc, v36, v147
	v_subrev_u32_e32 v36, 21, v154
	s_nop 0
	v_cndmask_b32_e32 v160, v134, v41, vcc
	v_cmp_le_i32_e32 vcc, v36, v147
	v_subrev_u32_e32 v36, 48, v154
	v_exp_f32_e32 v41, v53
	v_cndmask_b32_e32 v57, v134, v57, vcc
	v_cmp_le_i32_e32 vcc, v36, v147
	v_add_u32_e32 v36, -16, v154
	v_exp_f32_e32 v51, v57
	v_cndmask_b32_e32 v161, v134, v42, vcc
	v_cmp_le_i32_e32 vcc, v36, v147
	v_subrev_u32_e32 v36, 47, v154
	v_exp_f32_e32 v52, v161
	v_cndmask_b32_e32 v58, v134, v58, vcc
	v_cmp_le_i32_e32 vcc, v36, v147
	v_add_u32_e32 v36, -15, v154
	s_nop 0
	v_cndmask_b32_e32 v162, v134, v43, vcc
	v_cmp_le_i32_e32 vcc, v36, v147
	v_subrev_u32_e32 v36, 46, v154
	v_pk_add_f32 v[42:43], v[34:35], 0 op_sel_hi:[1,0]
	v_cndmask_b32_e32 v59, v134, v59, vcc
	v_cmp_le_i32_e32 vcc, v36, v147
	v_add_u32_e32 v36, -14, v154
	v_exp_f32_e32 v53, v162
	v_cndmask_b32_e32 v163, v134, v44, vcc
	v_cmp_le_i32_e32 vcc, v36, v147
	v_subrev_u32_e32 v36, 45, v154
	v_exp_f32_e32 v44, v157
	v_cndmask_b32_e32 v60, v134, v60, vcc
	v_cmp_le_i32_e32 vcc, v36, v147
	v_add_u32_e32 v36, -13, v154
	v_cvt_pk_bf16_f32 v157, v38, v39
	v_cndmask_b32_e32 v164, v134, v45, vcc
	v_cmp_le_i32_e32 vcc, v36, v147
	v_subrev_u32_e32 v36, 40, v154
	v_exp_f32_e32 v45, v158
	v_cndmask_b32_e32 v61, v134, v61, vcc
	v_cmp_le_i32_e32 vcc, v36, v147
	v_add_u32_e32 v36, -8, v154
	v_exp_f32_e32 v57, v164
	v_cndmask_b32_e32 v165, v134, v46, vcc
	v_cmp_le_i32_e32 vcc, v36, v147
	v_subrev_u32_e32 v36, 39, v154
	v_exp_f32_e32 v46, v54
	v_cndmask_b32_e32 v62, v134, v62, vcc
	v_cmp_le_i32_e32 vcc, v36, v147
	v_add_u32_e32 v36, -7, v154
	v_exp_f32_e32 v54, v58
	v_cndmask_b32_e32 v166, v134, v47, vcc
	v_cmp_le_i32_e32 vcc, v36, v147
	v_subrev_u32_e32 v36, 38, v154
	v_exp_f32_e32 v47, v55
	v_cndmask_b32_e32 v63, v134, v63, vcc
	v_cmp_le_i32_e32 vcc, v36, v147
	v_add_u32_e32 v36, -6, v154
	v_exp_f32_e32 v55, v59
	v_cndmask_b32_e32 v167, v134, v48, vcc
	v_cmp_le_i32_e32 vcc, v36, v147
	v_subrev_u32_e32 v36, 37, v154
	v_exp_f32_e32 v48, v159
	v_cndmask_b32_e32 v168, v134, v64, vcc
	v_cmp_le_i32_e32 vcc, v36, v147
	v_add_u32_e32 v36, -5, v154
	v_exp_f32_e32 v58, v60
	v_cndmask_b32_e32 v169, v134, v49, vcc
	v_cmp_le_i32_e32 vcc, v36, v147
	v_exp_f32_e32 v36, v50
	v_exp_f32_e32 v49, v160
	v_exp_f32_e32 v50, v56
	v_exp_f32_e32 v56, v163
	v_pk_add_f32 v[42:43], v[36:37], v[42:43]
	v_exp_f32_e32 v59, v61
	v_pk_add_f32 v[42:43], v[38:39], v[42:43]
	v_exp_f32_e32 v64, v167
	v_pk_add_f32 v[42:43], v[40:41], v[42:43]
	v_cvt_pk_bf16_f32 v167, v50, v51
	v_pk_add_f32 v[42:43], v[44:45], v[42:43]
	v_exp_f32_e32 v60, v165
	v_pk_add_f32 v[42:43], v[46:47], v[42:43]
	v_exp_f32_e32 v61, v166
	v_pk_add_f32 v[42:43], v[48:49], v[42:43]
	v_cvt_pk_bf16_f32 v160, v52, v53
	v_pk_add_f32 v[42:43], v[50:51], v[42:43]
	ds_read_b64_tr_b16 v[50:51],v151 offset:0
	v_exp_f32_e32 v62, v62
	v_pk_add_f32 v[42:43], v[52:53], v[42:43]
	ds_read_b64_tr_b16 v[52:53],v151 offset:512
	v_exp_f32_e32 v63, v63
	v_pk_add_f32 v[42:43], v[54:55], v[42:43]
	v_exp_f32_e32 v172, v168
	v_cvt_pk_bf16_f32 v168, v54, v55
	ds_read_b64_tr_b16 v[54:55],v151 offset:1024
	v_cndmask_b32_e32 v154, v134, v65, vcc
	v_pk_add_f32 v[42:43], v[56:57], v[42:43]
	v_exp_f32_e32 v65, v169
	v_cvt_pk_bf16_f32 v161, v56, v57
	ds_read_b64_tr_b16 v[56:57],v151 offset:1536
	v_pk_add_f32 v[42:43], v[58:59], v[42:43]
	v_exp_f32_e32 v173, v154
	v_cvt_pk_bf16_f32 v169, v58, v59
	ds_read_b64_tr_b16 v[58:59],v151 offset:2048
	v_pk_add_f32 v[42:43], v[60:61], v[42:43]
	v_cvt_pk_bf16_f32 v162, v60, v61
	ds_read_b64_tr_b16 v[60:61],v151 offset:2560
	v_pk_add_f32 v[42:43], v[62:63], v[42:43]
	v_cvt_pk_bf16_f32 v170, v62, v63
	ds_read_b64_tr_b16 v[62:63],v151 offset:3072
	v_pk_add_f32 v[42:43], v[64:65], v[42:43]
	v_cvt_pk_bf16_f32 v163, v64, v65
	ds_read_b64_tr_b16 v[64:65],v151 offset:3584
	v_pk_add_f32 v[42:43], v[172:173], v[42:43]
	s_waitcnt lgkmcnt(0)
	v_cvt_pk_bf16_f32 v158, v44, v45
	v_add_f32_e32 v42, v42, v43
	v_add_f32_e32 v154, v148, v42
	v_cvt_pk_bf16_f32 v159, v48, v49
	v_cvt_pk_bf16_f32 v164, v36, v37
	v_cvt_pk_bf16_f32 v165, v40, v41
	v_cvt_pk_bf16_f32 v166, v46, v47
	v_cvt_pk_bf16_f32 v171, v172, v173
	v_mfma_f32_32x32x16_bf16 v[2:17], v[156:159], v[50:53], v[2:17]
	ds_read_b64_tr_b16 v[172:173],v151 offset:4096
	ds_read_b64_tr_b16 v[174:175],v151 offset:4608
	ds_read_b64_tr_b16 v[176:177],v151 offset:5120
	ds_read_b64_tr_b16 v[178:179],v151 offset:5632
	ds_read_b64_tr_b16 v[180:181],v151 offset:6144
	ds_read_b64_tr_b16 v[182:183],v151 offset:6656
	ds_read_b64_tr_b16 v[184:185],v151 offset:7168
	v_mfma_f32_32x32x16_bf16 v[2:17], v[160:163], v[54:57], v[2:17]
	ds_read_b64_tr_b16 v[186:187],v151 offset:7680
	s_waitcnt lgkmcnt(0)
	v_mfma_f32_32x32x16_bf16 v[2:17], v[164:167], v[58:61], v[2:17]
	v_mfma_f32_32x32x16_bf16 v[2:17], v[168:171], v[62:65], v[2:17]
	v_mfma_f32_32x32x16_bf16 v[18:33], v[156:159], v[172:175], v[18:33]
	s_mov_b64 s[64:65], 0
	v_mfma_f32_32x32x16_bf16 v[18:33], v[160:163], v[176:179], v[18:33]
	v_mfma_f32_32x32x16_bf16 v[18:33], v[164:167], v[180:183], v[18:33]
	v_mfma_f32_32x32x16_bf16 v[18:33], v[168:171], v[184:187], v[18:33]

.LBB0_792:
	s_cmp_lg_u32 s48, 0
	v_fma_f32 v151, v150, s50, -v146
	s_cselect_b64 s[64:65], -1, 0
	v_cmp_nlt_f32_e64 s[66:67], v151, -v131
	v_fma_f32 v196, v150, s50, -v197
	v_cmp_lt_f32_e64 s[100:101], v196, -v131
	s_nop 3
	s_or_b64 s[98:99], s[98:99], s[100:101]
	s_and_b64 s[68:69], s[64:65], s[66:67]
	s_mov_b64 s[66:67], -1
	s_and_saveexec_b64 s[64:65], s[68:69]
	s_cbranch_execz .LBB0_776
	s_waitcnt lgkmcnt(0)
	s_barrier
	s_waitcnt vmcnt(4)
	s_nop 1
	v_add_f32_dpp v151, v141, v141 row_shl:1 row_mask:0xf bank_mask:0xf bound_ctrl:1
	s_nop 1
	v_add_f32_dpp v151, v151, v151 row_shl:2 row_mask:0xf bank_mask:0xf bound_ctrl:1
	s_nop 1
	v_add_f32_dpp v151, v151, v151 row_shl:4 row_mask:0xf bank_mask:0xf bound_ctrl:1
	s_nop 1
	v_add_f32_dpp v152, v151, v151 row_shl:8 row_mask:0xf bank_mask:0xf bound_ctrl:1
	s_nop 0
	v_readlane_b32 s28, v152, 16
	v_readlane_b32 s79, v152, 32
	v_readlane_b32 s77, v152, 48
	s_nop 0
	v_mul_f32_e32 v153, s79, v192
	v_fmac_f32_e32 v153, s28, v191
	v_fmac_f32_e32 v153, s77, v193
	v_add_f32_e32 v151, s76, v150
	v_add_f32_e32 v150, v152, v153
	v_add_f32_e32 v152, v151, v150
	s_lshl_b32 s28, s70, 8
	v_sub_f32_e32 v141, v152, v141
	s_add_i32 s76, s53, s28
	v_mul_f32_e32 v141, 0x3fb8aa3b, v141
	v_lshl_add_u32 v152, v137, 2, s76
	s_lshl_b32 s77, s70, 14
	ds_write_b32 v152, v141 offset:32768
	v_add_u32_e32 v141, s77, v143
	s_max_i32 s28, s48, 5
	ds_write_b128 v141, v[70:73]
	ds_write_b128 v141, v[82:85] offset:8192
	s_add_i32 s28, s28, -5
	s_waitcnt lgkmcnt(0)
	s_lshl_b64 s[66:67], s[28:29], 11
	v_lshl_add_u64 v[70:71], v[110:111], 0, s[66:67]
	global_load_dword v141, v[70:71], off
	s_lshl_b64 s[66:67], s[28:29], 16
	v_lshl_add_u64 v[82:83], v[106:107], 0, s[66:67]
	global_load_dwordx4 v[70:73], v[82:83], off
	v_lshl_add_u64 v[152:153], v[108:109], 0, s[66:67]
	global_load_dwordx4 v[82:85], v[152:153], off
	v_readfirstlane_b32 s79, v150
	s_and_b64 vcc, exec, s[12:13]
	s_cbranch_vccnz .LBB0_808
	s_and_b64 vcc, exec, s[98:99]
	s_cbranch_vccnz .LBB0_808
	s_add_i32 s28, s75, 0xffffff80
	s_cmp_gt_i32 s28, s73
	s_cbranch_scc1 .LBB0_808
	s_cmp_le_i32 s48, s72
	v_add_u32_e32 v150, s78, v144
	s_mov_b64 s[66:67], -1
	v_add_u32_e32 v152, s78, v145
	v_lshl_add_u32 v153, v142, 2, s71
	s_cbranch_scc0 .LBB0_805
; #define LAS __attribute__((address_space(3)))
; __device__ __forceinline__ void pv(f32x16* o, int vb, bf16x8 pa0, bf16x8 pa1, bf16x8 pa2, bf16x8 pa3) {
; #pragma unroll
;     for (int d0 = 0; d0 < 2; ++d0) { s16x4 lo[4], hi[4];
; #pragma unroll
;         for (int ks = 0; ks < 4; ++ks) {
; template <bool BAND>
; __device__ __forceinline__ void tile_body(f32x16* o, float& l_reg, const bf16x8* qr, const LAS unsigned char* kbs, const LAS float* wb, int vb, float ci, int hi, int keybase, int qabs) {
;     f32x16 p0, p1;
; #pragma unroll
;     for (int g4 = 0; g4 < 4; ++g4) {
;         const f32x4 ba = *(const LAS f32x4*)(wb + 8 * g4 + 4 * hi) + ci, bb = *(const LAS f32x4*)(wb + 32 + 8 * g4 + 4 * hi) + ci;
; #pragma unroll
;         for (int e = 0; e < 4; ++e) { p0[4 * g4 + e] = ba[e]; p1[4 * g4 + e] = bb[e]; }
;     }
; #pragma unroll
;     for (int d0 = 0; d0 < 4; ++d0) {
;         const bf16x8 b0 = *(const LAS bf16x8*)(kbs + d0 * 2048), b1 = *(const LAS bf16x8*)(kbs + d0 * 2048 + 512);
;         p0 = __builtin_amdgcn_mfma_f32_32x32x16_bf16(b0, qr[d0], p0, 0, 0, 0); p1 = __builtin_amdgcn_mfma_f32_32x32x16_bf16(b1, qr[d0], p1, 0, 0, 0); }
;     if (BAND) {
; #pragma unroll
;         for (int r = 0; r < 16; ++r) { const int key = keybase + 8 * (r >> 2) + (r & 3); if (key > qabs) p0[r] = -INFINITY; if (key + 32 > qabs) p1[r] = -INFINITY; }
;     }
;     f32x2 s2 = {0.f, 0.f};
; #pragma unroll
;     for (int r = 0; r < 16; r += 2) {
;         p0[r] = __builtin_amdgcn_exp2f(p0[r]); p0[r + 1] = __builtin_amdgcn_exp2f(p0[r + 1]); p1[r] = __builtin_amdgcn_exp2f(p1[r]); p1[r + 1] = __builtin_amdgcn_exp2f(p1[r + 1]);
;         s2 += (f32x2){p0[r], p0[r + 1]}; s2 += (f32x2){p1[r], p1[r + 1]}; }
;     l_reg += s2.x + s2.y;
;     u32x4 pw0, pw1, pw2, pw3;
;     pw0 = (u32x4){cvtpk(p0[0], p0[1]), cvtpk(p0[2], p0[3]), cvtpk(p0[4], p0[5]), cvtpk(p0[6], p0[7])};
;     pw1 = (u32x4){cvtpk(p0[8], p0[9]), cvtpk(p0[10], p0[11]), cvtpk(p0[12], p0[13]), cvtpk(p0[14], p0[15])};
;     pw2 = (u32x4){cvtpk(p1[0], p1[1]), cvtpk(p1[2], p1[3]), cvtpk(p1[4], p1[5]), cvtpk(p1[6], p1[7])};
;     pw3 = (u32x4){cvtpk(p1[8], p1[9]), cvtpk(p1[10], p1[11]), cvtpk(p1[12], p1[13]), cvtpk(p1[14], p1[15])};
;     pv(o, vb, __builtin_bit_cast(bf16x8, pw0), __builtin_bit_cast(bf16x8, pw1), __builtin_bit_cast(bf16x8, pw2), __builtin_bit_cast(bf16x8, pw3));
	ds_read_b128 v[34:37], v153 offset:32768
	ds_read_b128 v[38:41], v153 offset:32800
	ds_read_b128 v[42:45], v153 offset:32832
	ds_read_b128 v[46:49], v153 offset:32864
	ds_read_b128 v[50:53], v153 offset:32896
	ds_read_b128 v[54:57], v153 offset:32928
	ds_read_b128 v[58:61], v153 offset:32960
	ds_read_b128 v[62:65], v153 offset:32992
	ds_read_b128 v[154:157], v152
	ds_read_b128 v[158:161], v152 offset:512
	s_waitcnt lgkmcnt(6)
	ds_read_b128 v[210:213], v152 offset:2048
	ds_read_b128 v[214:217], v152 offset:2560
	ds_read_b128 v[218:221], v152 offset:4096
	ds_read_b128 v[222:225], v152 offset:4608
	ds_read_b128 v[226:229], v152 offset:6144
	ds_read_b128 v[230:233], v152 offset:6656
	v_pk_add_f32 v[48:49], v[126:127], v[48:49]
	v_pk_add_f32 v[44:45], v[122:123], v[44:45]
	v_pk_add_f32 v[40:41], v[118:119], v[40:41]
	v_pk_add_f32 v[36:37], v[114:115], v[36:37]
	v_pk_add_f32 v[46:47], v[124:125], v[46:47]
	v_pk_add_f32 v[42:43], v[120:121], v[42:43]
	v_pk_add_f32 v[38:39], v[116:117], v[38:39]
	v_pk_add_f32 v[34:35], v[112:113], v[34:35]
	s_waitcnt lgkmcnt(8)
	v_pk_add_f32 v[64:65], v[126:127], v[64:65]
	v_pk_add_f32 v[60:61], v[122:123], v[60:61]
	s_waitcnt lgkmcnt(7)
	v_mfma_f32_32x32x16_bf16 v[34:49], v[154:157], v[94:97], v[34:49]
	v_add_f32_e64 v56, v118, v56
	v_add_f32_e64 v57, v119, v57
	v_add_f32_e64 v52, v114, v52
	v_add_f32_e64 v53, v115, v53
	v_add_f32_e64 v62, v124, v62
	v_add_f32_e64 v63, v125, v63
	v_pk_add_f32 v[58:59], v[120:121], v[58:59]
	v_pk_add_f32 v[54:55], v[116:117], v[54:55]
	v_pk_add_f32 v[50:51], v[112:113], v[50:51]
	s_waitcnt lgkmcnt(6)
	s_nop 0
	v_mfma_f32_32x32x16_bf16 v[50:65], v[158:161], v[94:97], v[50:65]
	s_waitcnt lgkmcnt(5)
	v_mfma_f32_32x32x16_bf16 v[34:49], v[210:213], v[98:101], v[34:49]
	s_waitcnt lgkmcnt(4)
	v_mfma_f32_32x32x16_bf16 v[50:65], v[214:217], v[98:101], v[50:65]
	s_waitcnt lgkmcnt(3)
	v_mfma_f32_32x32x16_bf16 v[34:49], v[218:221], v[102:105], v[34:49]
	s_waitcnt lgkmcnt(2)
	v_mfma_f32_32x32x16_bf16 v[50:65], v[222:225], v[102:105], v[50:65]
	s_waitcnt lgkmcnt(1)
	v_mfma_f32_32x32x16_bf16 v[34:49], v[226:229], v[90:93], v[34:49]
	s_waitcnt lgkmcnt(0)
	v_mfma_f32_32x32x16_bf16 v[50:65], v[230:233], v[90:93], v[50:65]
	s_nop 9
	v_exp_f32_e32 v34, v34
	v_exp_f32_e32 v35, v35
	v_exp_f32_e32 v36, v36
	v_exp_f32_e32 v37, v37
	v_exp_f32_e32 v38, v38
	v_pk_add_f32 v[154:155], v[34:35], 0 op_sel_hi:[1,0]
	v_exp_f32_e32 v39, v39
	v_exp_f32_e32 v50, v50
	v_exp_f32_e32 v51, v51
	v_exp_f32_e32 v52, v52
	v_exp_f32_e32 v53, v53
	v_exp_f32_e32 v54, v54
	v_pk_add_f32 v[154:155], v[50:51], v[154:155]
	v_exp_f32_e32 v55, v55
	v_pk_add_f32 v[154:155], v[36:37], v[154:155]
	v_exp_f32_e32 v40, v40
	v_exp_f32_e32 v41, v41
	v_pk_add_f32 v[154:155], v[52:53], v[154:155]
	v_exp_f32_e32 v56, v56
	v_exp_f32_e32 v57, v57
	v_pk_add_f32 v[154:155], v[38:39], v[154:155]
	v_exp_f32_e32 v42, v42
	v_exp_f32_e32 v43, v43
	v_pk_add_f32 v[154:155], v[54:55], v[154:155]
	v_exp_f32_e32 v58, v58
	v_exp_f32_e32 v59, v59
	v_pk_add_f32 v[154:155], v[40:41], v[154:155]
	v_exp_f32_e32 v44, v44
	v_exp_f32_e32 v45, v45
	v_pk_add_f32 v[154:155], v[56:57], v[154:155]
	v_exp_f32_e32 v60, v60
	v_exp_f32_e32 v61, v61
	v_pk_add_f32 v[154:155], v[42:43], v[154:155]
	v_exp_f32_e32 v46, v46
	v_exp_f32_e32 v47, v47
	v_cvt_pk_bf16_f32 v164, v50, v51
	ds_read_b64_tr_b16 v[50:51],v150 offset:0
	v_pk_add_f32 v[154:155], v[58:59], v[154:155]
	v_exp_f32_e32 v62, v62
	v_exp_f32_e32 v63, v63
	v_cvt_pk_bf16_f32 v165, v52, v53
	ds_read_b64_tr_b16 v[52:53],v150 offset:512
	v_pk_add_f32 v[154:155], v[44:45], v[154:155]
	v_exp_f32_e32 v48, v48
	v_exp_f32_e32 v49, v49
	v_cvt_pk_bf16_f32 v166, v54, v55
	ds_read_b64_tr_b16 v[54:55],v150 offset:1024
	v_pk_add_f32 v[154:155], v[60:61], v[154:155]
	v_exp_f32_e32 v64, v64
	v_exp_f32_e32 v65, v65
	v_cvt_pk_bf16_f32 v167, v56, v57
	ds_read_b64_tr_b16 v[56:57],v150 offset:1536
	v_pk_add_f32 v[154:155], v[46:47], v[154:155]
	v_cvt_pk_bf16_f32 v168, v58, v59
	ds_read_b64_tr_b16 v[58:59],v150 offset:2048
	v_pk_add_f32 v[154:155], v[62:63], v[154:155]
	v_cvt_pk_bf16_f32 v169, v60, v61
	ds_read_b64_tr_b16 v[60:61],v150 offset:2560
	v_pk_add_f32 v[154:155], v[48:49], v[154:155]
	v_cvt_pk_bf16_f32 v170, v62, v63
	ds_read_b64_tr_b16 v[62:63],v150 offset:3072
	v_pk_add_f32 v[154:155], v[64:65], v[154:155]
	v_cvt_pk_bf16_f32 v171, v64, v65
	ds_read_b64_tr_b16 v[64:65],v150 offset:3584
	s_waitcnt lgkmcnt(0)
	v_add_f32_e32 v154, v154, v155
	v_add_f32_e32 v154, v148, v154
	v_cvt_pk_bf16_f32 v156, v34, v35
	v_cvt_pk_bf16_f32 v157, v36, v37
	v_cvt_pk_bf16_f32 v158, v38, v39
	v_cvt_pk_bf16_f32 v159, v40, v41
	v_cvt_pk_bf16_f32 v160, v42, v43
	v_cvt_pk_bf16_f32 v161, v44, v45
	v_cvt_pk_bf16_f32 v162, v46, v47
	v_cvt_pk_bf16_f32 v163, v48, v49
	v_mfma_f32_32x32x16_bf16 v[2:17], v[156:159], v[50:53], v[2:17]
	ds_read_b64_tr_b16 v[172:173],v150 offset:4096
	ds_read_b64_tr_b16 v[174:175],v150 offset:4608
	ds_read_b64_tr_b16 v[176:177],v150 offset:5120
	ds_read_b64_tr_b16 v[178:179],v150 offset:5632
	ds_read_b64_tr_b16 v[180:181],v150 offset:6144
	ds_read_b64_tr_b16 v[182:183],v150 offset:6656
	ds_read_b64_tr_b16 v[184:185],v150 offset:7168
	s_nop 0
	v_mfma_f32_32x32x16_bf16 v[2:17], v[160:163], v[54:57], v[2:17]
	ds_read_b64_tr_b16 v[186:187],v150 offset:7680
	s_waitcnt lgkmcnt(0)
	v_mfma_f32_32x32x16_bf16 v[2:17], v[164:167], v[58:61], v[2:17]
	v_mfma_f32_32x32x16_bf16 v[2:17], v[168:171], v[62:65], v[2:17]
	v_mfma_f32_32x32x16_bf16 v[18:33], v[156:159], v[172:175], v[18:33]
	s_mov_b64 s[66:67], 0
	v_mfma_f32_32x32x16_bf16 v[18:33], v[160:163], v[176:179], v[18:33]
	v_mfma_f32_32x32x16_bf16 v[18:33], v[164:167], v[180:183], v[18:33]
	v_mfma_f32_32x32x16_bf16 v[18:33], v[168:171], v[184:187], v[18:33]

.LBB0_808:
	s_cmp_lg_u32 s48, 1
	v_fma_f32 v150, v151, s50, -v146
	s_cselect_b64 s[66:67], -1, 0
	v_cmp_nlt_f32_e64 s[68:69], v150, -v131
	v_fma_f32 v196, v151, s50, -v197
	v_cmp_lt_f32_e64 s[100:101], v196, -v131
	s_nop 3
	s_or_b64 s[98:99], s[98:99], s[100:101]
	s_and_b64 s[70:71], s[66:67], s[68:69]
	s_mov_b64 s[68:69], -1
	s_and_saveexec_b64 s[66:67], s[70:71]
	s_cbranch_execz .LBB0_775
	s_waitcnt lgkmcnt(0)
	s_barrier
	s_waitcnt vmcnt(4)
	s_nop 1
	v_add_f32_dpp v150, v139, v139 row_shl:1 row_mask:0xf bank_mask:0xf bound_ctrl:1
	s_nop 1
	v_add_f32_dpp v150, v150, v150 row_shl:2 row_mask:0xf bank_mask:0xf bound_ctrl:1
	s_nop 1
	v_add_f32_dpp v150, v150, v150 row_shl:4 row_mask:0xf bank_mask:0xf bound_ctrl:1
	s_nop 1
	v_add_f32_dpp v150, v150, v150 row_shl:8 row_mask:0xf bank_mask:0xf bound_ctrl:1
	s_nop 0
	v_readlane_b32 s28, v150, 16
	v_readlane_b32 s80, v150, 32
	v_readlane_b32 s78, v150, 48
	s_nop 0
	v_mul_f32_e32 v152, s80, v192
	v_fmac_f32_e32 v152, s28, v191
	v_fmac_f32_e32 v152, s78, v193
	v_add_f32_e32 v151, s79, v151
	v_add_f32_e32 v150, v150, v152
	v_add_f32_e32 v152, v151, v150
	v_sub_f32_e32 v139, v152, v139
	v_mul_f32_e32 v139, 0x3fb8aa3b, v139
	s_max_i32 s28, s48, 6
	ds_write_b32 v0, v139 offset:32768
	ds_write_b128 v149, v[78:81]
	ds_write_b128 v149, v[86:89] offset:8192
	s_add_i32 s28, s28, -6
	s_waitcnt lgkmcnt(0)
	s_lshl_b64 s[68:69], s[28:29], 11
	v_lshl_add_u64 v[78:79], v[110:111], 0, s[68:69]
	global_load_dword v139, v[78:79], off
	s_lshl_b64 s[68:69], s[28:29], 16
	v_lshl_add_u64 v[86:87], v[106:107], 0, s[68:69]
	global_load_dwordx4 v[78:81], v[86:87], off
	v_lshl_add_u64 v[152:153], v[108:109], 0, s[68:69]
	global_load_dwordx4 v[86:89], v[152:153], off
	v_readfirstlane_b32 s70, v150
	s_andn2_b64 vcc, exec, s[60:61]
	s_mov_b64 s[68:69], -1
	s_cbranch_vccnz .LBB0_819
	s_add_i32 s28, s75, 0xffffff40
	s_mov_b64 s[68:69], 0
